# stack5: + per-tile preheader vmcnt(0) removed before the peeled K-loops
# baseline (speedup 1.0000x reference)
; #define PG8_STAGE(bufoff, gbase, voff) do { _Pragma("unroll") for (int _i = 0; _i < 2; ++_i) \
;         __builtin_amdgcn_global_load_lds((const unsigned*)((const char*)(gbase) + (voff)[_i]), (PG8_LAS unsigned*)(lds + (bufoff) + ldsw + _i * 8192), 16, 0, 0); } while (0)
; #define PG8_LDA(dst, b, h) do { _Pragma("unroll") for (int m = 0; m < 4; ++m) _Pragma("unroll") for (int k = 0; k < 2; ++k) dst[m][k] = *(const PG8_LAS bf16x8*)(lds + PG8_SA(b, h) + aoff + m * 2048 + k * 1024); } while (0)
; #define PG8_WAIT_V(n) asm volatile("s_waitcnt vmcnt(" #n ")" ::: "memory")
; #define PG8_WAIT_L(n) asm volatile("s_waitcnt lgkmcnt(" #n ")" ::: "memory")
; #define PG8_BAR __builtin_amdgcn_s_barrier()
; template <class Epi, class Sched, bool ALIGN_EPI = false, bool SP2 = false>
; __device__ __forceinline__ void gemm_phase(PG8_LAS unsigned char* lds, const Gemm g, const Sched& S, const Epi& E, int tid_in) {
;     ...
;     for (;;) {
;         const bool has_next = S.next(ui + 1, nxt);
;         const char* nA = has_next ? g.apanel(nxt.pm, tstep) : cA; const char* nB = has_next ? (const char*)g.Bt + (size_t)nxt.pn * tstep : cB;
;         for (int seg = 0; seg < (Epi::KSEG ? 3 : 1); ++seg) {
;         if constexpr (Epi::KSEG) { if (seg > 0) E.kscale(acc, seg, cur, wr, fr); }
;         const int tb_ = Epi::KSEG ? (seg == 0 ? 0 : (seg == 1 ? 8 : 12)) : 0, te_ = Epi::KSEG ? (seg == 0 ? 8 : (seg == 1 ? 12 : nt)) : nt;
; #pragma unroll 1
;         for (int t = tb_; t < te_; t += 2) {
;             const bool last = (t == nt - 2);
;             const char* a1 = cA + (size_t)(t + 1) * kstep;
;             const char* a2 = last ? nA : cA + (size_t)(t + 2) * kstep; const char* b2 = last ? nB : cB + (size_t)(t + 2) * kstep;
;             const char* a3 = a2 + kstep; const char* b3 = b2 + kstep;
;             if (last && has_next) S.a_ready(nxt);
;             if constexpr (SP2) {
;             PG8_LDB(B0, 0, 0); PG8_LDB(B1, 0, 1); PG8_SCHED; PG8_LDA(At, 0, 0); PG8_STAGE(PG8_SA(1, 1), a1 + hstep, voffA);
;             PG8_WAIT_V(8); PG8_WAIT_L(0); PG8_BAR; PG8_MMA(0, 0, At, B0); PG8_MMA(0, 1, At, B1); PG8_BAR; PG8_SCHED;
;             PG8_LDA(At, 0, 1); PG8_STAGE(PG8_SB(0, 0), b2, voffB); PG8_STAGE(PG8_SB(0, 1), b2 + hstep, voffB); PG8_STAGE(PG8_SA(0, 0), a2, voffA);
;             PG8_WAIT_V(8); PG8_WAIT_L(0); PG8_BAR; PG8_MMA(1, 0, At, B0); PG8_MMA(1, 1, At, B1); PG8_BAR; PG8_SCHED;
.LBB0_74:
	s_add_u32 s30, s24, 0x100
	s_addc_u32 s31, s25, 0
	s_mov_b32 s44, -2
	s_add_u32 s24, s22, 0x100
	s_addc_u32 s25, s23, 0
	s_add_i32 s45, 0, 0x10000
	s_cmp_eq_u32 s44, 40
	s_cselect_b32 s29, s61, s25
	s_cselect_b32 s28, s60, s24
	s_cselect_b32 s27, s21, s31
	s_cselect_b32 s26, s20, s30
	s_add_i32 s48, 0, 0x14000
	v_add_u32_e32 v152, s45, v159
	v_add_u32_e32 v156, s48, v159
	ds_read_b128 v[130:133], v152
	ds_read_b128 v[134:137], v152 offset:1024
	ds_read_b128 v[148:151], v152 offset:2048
	ds_read_b128 v[152:155], v152 offset:3072
	ds_read_b128 v[180:183], v156
	ds_read_b128 v[184:187], v156 offset:1024
	ds_read_b128 v[188:191], v156 offset:2048
	ds_read_b128 v[192:195], v156 offset:3072
	v_lshl_add_u64 v[156:157], s[22:23], 0, v[144:145]
	s_add_i32 m0, s62, 0xc000
	ds_read_b128 v[196:199], v178
	ds_read_b128 v[200:203], v178 offset:1024
	ds_read_b128 v[204:207], v178 offset:2048
	ds_read_b128 v[208:211], v178 offset:3072
	ds_read_b128 v[212:215], v178 offset:4096
	ds_read_b128 v[216:219], v178 offset:5120
	ds_read_b128 v[220:223], v178 offset:6144
	ds_read_b128 v[242:245], v178 offset:7168
	global_load_lds_dwordx4 v[156:157], off
	v_lshl_add_u64 v[156:157], s[22:23], 0, v[146:147]
	s_add_i32 m0, s62, 0xe000
	s_nop 0
	global_load_lds_dwordx4 v[156:157], off
	s_waitcnt vmcnt(8)
	s_waitcnt lgkmcnt(0)
	s_barrier
	s_setprio 1
	s_waitcnt lgkmcnt(0)
	v_mfma_f32_16x16x32_bf16 v[126:129], v[130:133], v[196:199], 0
	v_mfma_f32_16x16x32_bf16 v[122:125], v[148:151], v[196:199], 0
	v_mfma_f32_16x16x32_bf16 v[110:113], v[130:133], v[204:207], 0
	v_mfma_f32_16x16x32_bf16 v[106:109], v[148:151], v[204:207], 0
	v_mfma_f32_16x16x32_bf16 v[94:97], v[130:133], v[212:215], 0
	v_mfma_f32_16x16x32_bf16 v[90:93], v[148:151], v[212:215], 0
	v_mfma_f32_16x16x32_bf16 v[78:81], v[130:133], v[220:223], 0
	v_mfma_f32_16x16x32_bf16 v[74:77], v[148:151], v[220:223], 0
	v_mfma_f32_16x16x32_bf16 v[126:129], v[134:137], v[200:203], v[126:129]
	v_mfma_f32_16x16x32_bf16 v[122:125], v[152:155], v[200:203], v[122:125]
	v_mfma_f32_16x16x32_bf16 v[110:113], v[134:137], v[208:211], v[110:113]
	v_mfma_f32_16x16x32_bf16 v[106:109], v[152:155], v[208:211], v[106:109]
	v_mfma_f32_16x16x32_bf16 v[94:97], v[134:137], v[216:219], v[94:97]
	v_mfma_f32_16x16x32_bf16 v[90:93], v[152:155], v[216:219], v[90:93]
	v_mfma_f32_16x16x32_bf16 v[78:81], v[134:137], v[242:245], v[78:81]
	v_mfma_f32_16x16x32_bf16 v[74:77], v[152:155], v[242:245], v[74:77]
	v_mfma_f32_16x16x32_bf16 v[118:121], v[180:183], v[196:199], 0
	v_mfma_f32_16x16x32_bf16 v[114:117], v[188:191], v[196:199], 0
	v_mfma_f32_16x16x32_bf16 v[102:105], v[180:183], v[204:207], 0
	v_mfma_f32_16x16x32_bf16 v[98:101], v[188:191], v[204:207], 0
	v_mfma_f32_16x16x32_bf16 v[86:89], v[180:183], v[212:215], 0
	v_mfma_f32_16x16x32_bf16 v[82:85], v[188:191], v[212:215], 0
	v_mfma_f32_16x16x32_bf16 v[70:73], v[180:183], v[220:223], 0
	v_mfma_f32_16x16x32_bf16 v[66:69], v[188:191], v[220:223], 0
	v_mfma_f32_16x16x32_bf16 v[118:121], v[184:187], v[200:203], v[118:121]
	v_mfma_f32_16x16x32_bf16 v[114:117], v[192:195], v[200:203], v[114:117]
	v_mfma_f32_16x16x32_bf16 v[102:105], v[184:187], v[208:211], v[102:105]
	v_mfma_f32_16x16x32_bf16 v[98:101], v[192:195], v[208:211], v[98:101]
	v_mfma_f32_16x16x32_bf16 v[86:89], v[184:187], v[216:219], v[86:89]
	v_mfma_f32_16x16x32_bf16 v[82:85], v[192:195], v[216:219], v[82:85]
	v_mfma_f32_16x16x32_bf16 v[70:73], v[184:187], v[242:245], v[70:73]
	v_mfma_f32_16x16x32_bf16 v[66:69], v[192:195], v[242:245], v[66:69]
	s_setprio 0
	s_barrier
	s_add_i32 s22, s45, s37
	v_lshl_add_u64 v[156:157], s[26:27], 0, v[64:65]
	s_mov_b32 m0, s22
	ds_read_b128 v[196:199], v178 offset:16384
	ds_read_b128 v[200:203], v178 offset:17408
	ds_read_b128 v[204:207], v178 offset:18432
	ds_read_b128 v[208:211], v178 offset:19456
	ds_read_b128 v[212:215], v178 offset:20480
	ds_read_b128 v[216:219], v178 offset:21504
	ds_read_b128 v[220:223], v178 offset:22528
	ds_read_b128 v[242:245], v178 offset:23552
	global_load_lds_dwordx4 v64, s[26:27]
	s_add_i32 m0, s22, 0x2000
	s_add_u32 s22, s26, 0xb0000
	v_lshl_add_u64 v[172:173], s[26:27], 0, v[142:143]
	s_addc_u32 s23, s27, 0
	s_add_i32 s45, s48, s37
	global_load_lds_dwordx4 v142, s[26:27]
	s_mov_b32 m0, s45
	v_lshl_add_u64 v[232:233], s[28:29], 0, v[140:141]
	global_load_lds_dwordx4 v64, s[22:23]
	s_add_i32 m0, s45, 0x2000
	s_nop 0
	global_load_lds_dwordx4 v142, s[22:23]
	v_lshl_add_u64 v[224:225], s[28:29], 0, v[138:139]
	s_mov_b32 m0, s62
	s_nop 0
	global_load_lds_dwordx4 v138, s[28:29]
	s_mov_b32 m0, s63
	s_nop 0
	global_load_lds_dwordx4 v140, s[28:29]
	s_waitcnt vmcnt(8)
	s_waitcnt lgkmcnt(0)
	s_barrier
; #define PG8_STAGE(bufoff, gbase, voff) do { _Pragma("unroll") for (int _i = 0; _i < 2; ++_i) \
;         __builtin_amdgcn_global_load_lds((const unsigned*)((const char*)(gbase) + (voff)[_i]), (PG8_LAS unsigned*)(lds + (bufoff) + ldsw + _i * 8192), 16, 0, 0); } while (0)
; #define PG8_LDA(dst, b, h) do { _Pragma("unroll") for (int m = 0; m < 4; ++m) _Pragma("unroll") for (int k = 0; k < 2; ++k) dst[m][k] = *(const PG8_LAS bf16x8*)(lds + PG8_SA(b, h) + aoff + m * 2048 + k * 1024); } while (0)
; #define PG8_LDB(dst, b, h) do { _Pragma("unroll") for (int n = 0; n < 2; ++n) _Pragma("unroll") for (int k = 0; k < 2; ++k) dst[n][k] = *(const PG8_LAS bf16x8*)(lds + PG8_SB(b, h) + boff + n * 2048 + k * 1024); } while (0)
; #define PG8_MMA(ai, bj, At, Bt) do { __builtin_amdgcn_s_setprio(1); _Pragma("unroll") for (int m = 0; m < 4; ++m) _Pragma("unroll") for (int n = 0; n < 2; ++n) _Pragma("unroll") for (int k = 0; k < 2; ++k) \
;         acc[ai][bj][m][n] = __builtin_amdgcn_mfma_f32_16x16x32_bf16(Bt[n][k], At[m][k], acc[ai][bj][m][n], 0, 0, 0); __builtin_amdgcn_s_setprio(0); } while (0)
; #define PG8_WAIT_V(n) asm volatile("s_waitcnt vmcnt(" #n ")" ::: "memory")
; #define PG8_WAIT_L(n) asm volatile("s_waitcnt lgkmcnt(" #n ")" ::: "memory")
; #define PG8_BAR __builtin_amdgcn_s_barrier()
; #define PG8_SCHED __builtin_amdgcn_sched_barrier(0)
; template <class Epi, class Sched, bool ALIGN_EPI = false, bool SP2 = false>
; __device__ __forceinline__ void gemm_phase(PG8_LAS unsigned char* lds, const Gemm g, const Sched& S, const Epi& E, int tid_in) {
;     ...
;             PG8_WAIT_V(8); PG8_WAIT_L(0); PG8_BAR; PG8_MMA(1, 0, At, B0); PG8_MMA(1, 1, At, B1); PG8_BAR; PG8_SCHED;
;             PG8_LDB(B0, 1, 0); PG8_LDB(B1, 1, 1); PG8_SCHED; PG8_LDA(At, 1, 0); PG8_STAGE(PG8_SA(0, 1), a2 + hstep, voffA);
;             PG8_WAIT_V(8); PG8_WAIT_L(0); PG8_BAR; PG8_MMA(0, 0, At, B0); PG8_MMA(0, 1, At, B1); PG8_BAR; PG8_SCHED;
	s_setprio 1
	s_waitcnt lgkmcnt(0)
	v_mfma_f32_16x16x32_bf16 v[60:63], v[130:133], v[196:199], 0
	v_mfma_f32_16x16x32_bf16 v[56:59], v[148:151], v[196:199], 0
	v_mfma_f32_16x16x32_bf16 v[44:47], v[130:133], v[204:207], 0
	v_mfma_f32_16x16x32_bf16 v[40:43], v[148:151], v[204:207], 0
	v_mfma_f32_16x16x32_bf16 v[28:31], v[130:133], v[212:215], 0
	v_mfma_f32_16x16x32_bf16 v[24:27], v[148:151], v[212:215], 0
	v_mfma_f32_16x16x32_bf16 v[12:15], v[130:133], v[220:223], 0
	v_mfma_f32_16x16x32_bf16 v[8:11], v[148:151], v[220:223], 0
	v_mfma_f32_16x16x32_bf16 v[60:63], v[134:137], v[200:203], v[60:63]
	v_mfma_f32_16x16x32_bf16 v[56:59], v[152:155], v[200:203], v[56:59]
	v_mfma_f32_16x16x32_bf16 v[44:47], v[134:137], v[208:211], v[44:47]
	v_mfma_f32_16x16x32_bf16 v[40:43], v[152:155], v[208:211], v[40:43]
	v_mfma_f32_16x16x32_bf16 v[28:31], v[134:137], v[216:219], v[28:31]
	v_mfma_f32_16x16x32_bf16 v[24:27], v[152:155], v[216:219], v[24:27]
	v_mfma_f32_16x16x32_bf16 v[12:15], v[134:137], v[242:245], v[12:15]
	v_mfma_f32_16x16x32_bf16 v[8:11], v[152:155], v[242:245], v[8:11]
	v_mfma_f32_16x16x32_bf16 v[52:55], v[180:183], v[196:199], 0
	v_mfma_f32_16x16x32_bf16 v[48:51], v[188:191], v[196:199], 0
	v_mfma_f32_16x16x32_bf16 v[36:39], v[180:183], v[204:207], 0
	v_mfma_f32_16x16x32_bf16 v[32:35], v[188:191], v[204:207], 0
	v_mfma_f32_16x16x32_bf16 v[20:23], v[180:183], v[212:215], 0
	v_mfma_f32_16x16x32_bf16 v[16:19], v[188:191], v[212:215], 0
	v_mfma_f32_16x16x32_bf16 v[4:7], v[180:183], v[220:223], 0
	v_mfma_f32_16x16x32_bf16 v[0:3], v[188:191], v[220:223], 0
	v_mfma_f32_16x16x32_bf16 v[52:55], v[184:187], v[200:203], v[52:55]
	v_mfma_f32_16x16x32_bf16 v[48:51], v[192:195], v[200:203], v[48:51]
	v_mfma_f32_16x16x32_bf16 v[36:39], v[184:187], v[208:211], v[36:39]
	v_mfma_f32_16x16x32_bf16 v[32:35], v[192:195], v[208:211], v[32:35]
	v_mfma_f32_16x16x32_bf16 v[20:23], v[184:187], v[216:219], v[20:23]
	v_mfma_f32_16x16x32_bf16 v[16:19], v[192:195], v[216:219], v[16:19]
	v_mfma_f32_16x16x32_bf16 v[4:7], v[184:187], v[242:245], v[4:7]
	v_mfma_f32_16x16x32_bf16 v[0:3], v[192:195], v[242:245], v[0:3]
	s_setprio 0
	s_barrier
	s_add_i32 s45, 0, 0x18000
	s_add_i32 s48, 0, 0x1c000
	v_add_u32_e32 v152, s45, v159
	v_add_u32_e32 v179, s48, v159
	ds_read_b128 v[130:133], v152
	ds_read_b128 v[134:137], v152 offset:1024
	ds_read_b128 v[148:151], v152 offset:2048
	ds_read_b128 v[152:155], v152 offset:3072
	ds_read_b128 v[180:183], v179
	ds_read_b128 v[184:187], v179 offset:1024
	ds_read_b128 v[188:191], v179 offset:2048
	ds_read_b128 v[192:195], v179 offset:3072
	s_add_u32 s22, s28, 0xb0000
	s_addc_u32 s23, s29, 0
	s_mov_b32 m0, s66
	ds_read_b128 v[196:199], v178 offset:32768
	ds_read_b128 v[200:203], v178 offset:33792
	ds_read_b128 v[204:207], v178 offset:34816
	ds_read_b128 v[208:211], v178 offset:35840
	ds_read_b128 v[212:215], v178 offset:36864
	ds_read_b128 v[216:219], v178 offset:37888
	ds_read_b128 v[220:223], v178 offset:38912
	ds_read_b128 v[242:245], v178 offset:39936
	global_load_lds_dwordx4 v138, s[22:23]
	s_mov_b32 m0, s67
	s_nop 0
	global_load_lds_dwordx4 v140, s[22:23]
	s_waitcnt vmcnt(8)
	s_waitcnt lgkmcnt(0)
	s_barrier
	s_setprio 1
	s_waitcnt lgkmcnt(0)
	v_mfma_f32_16x16x32_bf16 v[126:129], v[130:133], v[196:199], v[126:129]
	v_mfma_f32_16x16x32_bf16 v[122:125], v[148:151], v[196:199], v[122:125]
	v_mfma_f32_16x16x32_bf16 v[110:113], v[130:133], v[204:207], v[110:113]
	v_mfma_f32_16x16x32_bf16 v[106:109], v[148:151], v[204:207], v[106:109]
	v_mfma_f32_16x16x32_bf16 v[94:97], v[130:133], v[212:215], v[94:97]
	v_mfma_f32_16x16x32_bf16 v[90:93], v[148:151], v[212:215], v[90:93]
	v_mfma_f32_16x16x32_bf16 v[78:81], v[130:133], v[220:223], v[78:81]
	v_mfma_f32_16x16x32_bf16 v[74:77], v[148:151], v[220:223], v[74:77]
	v_mfma_f32_16x16x32_bf16 v[126:129], v[134:137], v[200:203], v[126:129]
	v_mfma_f32_16x16x32_bf16 v[122:125], v[152:155], v[200:203], v[122:125]
	v_mfma_f32_16x16x32_bf16 v[110:113], v[134:137], v[208:211], v[110:113]
	v_mfma_f32_16x16x32_bf16 v[106:109], v[152:155], v[208:211], v[106:109]
	v_mfma_f32_16x16x32_bf16 v[94:97], v[134:137], v[216:219], v[94:97]
	v_mfma_f32_16x16x32_bf16 v[90:93], v[152:155], v[216:219], v[90:93]
	v_mfma_f32_16x16x32_bf16 v[78:81], v[134:137], v[242:245], v[78:81]
	v_mfma_f32_16x16x32_bf16 v[74:77], v[152:155], v[242:245], v[74:77]
	v_mfma_f32_16x16x32_bf16 v[118:121], v[180:183], v[196:199], v[118:121]
	v_mfma_f32_16x16x32_bf16 v[114:117], v[188:191], v[196:199], v[114:117]
	v_mfma_f32_16x16x32_bf16 v[102:105], v[180:183], v[204:207], v[102:105]
	v_mfma_f32_16x16x32_bf16 v[98:101], v[188:191], v[204:207], v[98:101]
	v_mfma_f32_16x16x32_bf16 v[86:89], v[180:183], v[212:215], v[86:89]
	v_mfma_f32_16x16x32_bf16 v[82:85], v[188:191], v[212:215], v[82:85]
	v_mfma_f32_16x16x32_bf16 v[70:73], v[180:183], v[220:223], v[70:73]
	v_mfma_f32_16x16x32_bf16 v[66:69], v[188:191], v[220:223], v[66:69]
	v_mfma_f32_16x16x32_bf16 v[118:121], v[184:187], v[200:203], v[118:121]
	v_mfma_f32_16x16x32_bf16 v[114:117], v[192:195], v[200:203], v[114:117]
	v_mfma_f32_16x16x32_bf16 v[102:105], v[184:187], v[208:211], v[102:105]
	v_mfma_f32_16x16x32_bf16 v[98:101], v[192:195], v[208:211], v[98:101]
	v_mfma_f32_16x16x32_bf16 v[86:89], v[184:187], v[216:219], v[86:89]
	v_mfma_f32_16x16x32_bf16 v[82:85], v[192:195], v[216:219], v[82:85]
	v_mfma_f32_16x16x32_bf16 v[70:73], v[184:187], v[242:245], v[70:73]
	v_mfma_f32_16x16x32_bf16 v[66:69], v[192:195], v[242:245], v[66:69]
	s_setprio 0
	s_barrier
; #define PG8_STAGE(bufoff, gbase, voff) do { _Pragma("unroll") for (int _i = 0; _i < 2; ++_i) \
;         __builtin_amdgcn_global_load_lds((const unsigned*)((const char*)(gbase) + (voff)[_i]), (PG8_LAS unsigned*)(lds + (bufoff) + ldsw + _i * 8192), 16, 0, 0); } while (0)
; #define PG8_LDA(dst, b, h) do { _Pragma("unroll") for (int m = 0; m < 4; ++m) _Pragma("unroll") for (int k = 0; k < 2; ++k) dst[m][k] = *(const PG8_LAS bf16x8*)(lds + PG8_SA(b, h) + aoff + m * 2048 + k * 1024); } while (0)
; #define PG8_MMA(ai, bj, At, Bt) do { __builtin_amdgcn_s_setprio(1); _Pragma("unroll") for (int m = 0; m < 4; ++m) _Pragma("unroll") for (int n = 0; n < 2; ++n) _Pragma("unroll") for (int k = 0; k < 2; ++k) \
;         acc[ai][bj][m][n] = __builtin_amdgcn_mfma_f32_16x16x32_bf16(Bt[n][k], At[m][k], acc[ai][bj][m][n], 0, 0, 0); __builtin_amdgcn_s_setprio(0); } while (0)
; #define PG8_WAIT_V(n) asm volatile("s_waitcnt vmcnt(" #n ")" ::: "memory")
; #define PG8_WAIT_L(n) asm volatile("s_waitcnt lgkmcnt(" #n ")" ::: "memory")
; #define PG8_BAR __builtin_amdgcn_s_barrier()
; #define PG8_SCHED __builtin_amdgcn_sched_barrier(0)
; template <class Epi, class Sched, bool ALIGN_EPI = false, bool SP2 = false>
; __device__ __forceinline__ void gemm_phase(PG8_LAS unsigned char* lds, const Gemm g, const Sched& S, const Epi& E, int tid_in) {
;     ...
;         for (int t = tb_; t < te_; t += 2) {
;     ...
;             PG8_LDA(At, 1, 1); PG8_STAGE(PG8_SB(1, 0), b3, voffB); PG8_STAGE(PG8_SB(1, 1), b3 + hstep, voffB); PG8_STAGE(PG8_SA(1, 0), a3, voffA);
;             PG8_WAIT_V(8); PG8_WAIT_L(0); PG8_BAR; PG8_MMA(1, 0, At, B0); PG8_MMA(1, 1, At, B1); PG8_BAR; PG8_SCHED;
	s_add_i32 s22, s45, s37
	s_mov_b32 m0, s22
	ds_read_b128 v[196:199], v178 offset:49152
	ds_read_b128 v[200:203], v178 offset:50176
	ds_read_b128 v[204:207], v178 offset:51200
	ds_read_b128 v[208:211], v178 offset:52224
	ds_read_b128 v[212:215], v178 offset:53248
	ds_read_b128 v[216:219], v178 offset:54272
	ds_read_b128 v[220:223], v178 offset:55296
	ds_read_b128 v[242:245], v178 offset:56320
	s_add_u32 s98, s26, 0x80
	s_addc_u32 s99, s27, 0
	global_load_lds_dwordx4 v64, s[98:99]
	s_add_i32 m0, s22, 0x2000
	s_add_u32 s22, s26, 0xb0080
	v_lshl_add_u64 v[156:157], v[172:173], 0, s[92:93]
	s_addc_u32 s23, s27, 0
	s_add_i32 s26, s48, s37
	global_load_lds_dwordx4 v[156:157], off
	s_mov_b32 m0, s26
	s_nop 0
	global_load_lds_dwordx4 v64, s[22:23]
	s_add_i32 m0, s26, 0x2000
	s_nop 0
	global_load_lds_dwordx4 v142, s[22:23]
	s_mov_b32 m0, s69
	s_nop 0
	s_add_u32 s98, s28, 0x80
	s_addc_u32 s99, s29, 0
	global_load_lds_dwordx4 v138, s[98:99]
	s_mov_b32 m0, s74
	s_nop 0
	s_add_u32 s98, s28, 0x80
	s_addc_u32 s99, s29, 0
	global_load_lds_dwordx4 v140, s[98:99]
	s_waitcnt vmcnt(8)
	s_waitcnt lgkmcnt(0)
	s_barrier
	s_setprio 1
	s_waitcnt lgkmcnt(0)
	v_mfma_f32_16x16x32_bf16 v[60:63], v[130:133], v[196:199], v[60:63]
	v_mfma_f32_16x16x32_bf16 v[56:59], v[148:151], v[196:199], v[56:59]
	v_mfma_f32_16x16x32_bf16 v[44:47], v[130:133], v[204:207], v[44:47]
	v_mfma_f32_16x16x32_bf16 v[40:43], v[148:151], v[204:207], v[40:43]
	v_mfma_f32_16x16x32_bf16 v[28:31], v[130:133], v[212:215], v[28:31]
	v_mfma_f32_16x16x32_bf16 v[24:27], v[148:151], v[212:215], v[24:27]
	v_mfma_f32_16x16x32_bf16 v[12:15], v[130:133], v[220:223], v[12:15]
	v_mfma_f32_16x16x32_bf16 v[8:11], v[148:151], v[220:223], v[8:11]
	v_mfma_f32_16x16x32_bf16 v[60:63], v[134:137], v[200:203], v[60:63]
	v_mfma_f32_16x16x32_bf16 v[56:59], v[152:155], v[200:203], v[56:59]
	v_mfma_f32_16x16x32_bf16 v[44:47], v[134:137], v[208:211], v[44:47]
	v_mfma_f32_16x16x32_bf16 v[40:43], v[152:155], v[208:211], v[40:43]
	v_mfma_f32_16x16x32_bf16 v[28:31], v[134:137], v[216:219], v[28:31]
	v_mfma_f32_16x16x32_bf16 v[24:27], v[152:155], v[216:219], v[24:27]
	v_mfma_f32_16x16x32_bf16 v[12:15], v[134:137], v[242:245], v[12:15]
	v_mfma_f32_16x16x32_bf16 v[8:11], v[152:155], v[242:245], v[8:11]
	v_mfma_f32_16x16x32_bf16 v[52:55], v[180:183], v[196:199], v[52:55]
	v_mfma_f32_16x16x32_bf16 v[48:51], v[188:191], v[196:199], v[48:51]
	v_mfma_f32_16x16x32_bf16 v[36:39], v[180:183], v[204:207], v[36:39]
	v_mfma_f32_16x16x32_bf16 v[32:35], v[188:191], v[204:207], v[32:35]
	v_mfma_f32_16x16x32_bf16 v[20:23], v[180:183], v[212:215], v[20:23]
	v_mfma_f32_16x16x32_bf16 v[16:19], v[188:191], v[212:215], v[16:19]
	v_mfma_f32_16x16x32_bf16 v[4:7], v[180:183], v[220:223], v[4:7]
	v_mfma_f32_16x16x32_bf16 v[0:3], v[188:191], v[220:223], v[0:3]
	v_mfma_f32_16x16x32_bf16 v[52:55], v[184:187], v[200:203], v[52:55]
	v_mfma_f32_16x16x32_bf16 v[48:51], v[192:195], v[200:203], v[48:51]
	v_mfma_f32_16x16x32_bf16 v[36:39], v[184:187], v[208:211], v[36:39]
	v_mfma_f32_16x16x32_bf16 v[32:35], v[192:195], v[208:211], v[32:35]
	v_mfma_f32_16x16x32_bf16 v[20:23], v[184:187], v[216:219], v[20:23]
	v_mfma_f32_16x16x32_bf16 v[16:19], v[192:195], v[216:219], v[16:19]
	v_mfma_f32_16x16x32_bf16 v[4:7], v[184:187], v[242:245], v[4:7]
	v_mfma_f32_16x16x32_bf16 v[0:3], v[192:195], v[242:245], v[0:3]
	s_setprio 0
	s_barrier
	s_add_i32 s44, s44, 2
	s_add_u32 s30, s30, 0x100
	s_addc_u32 s31, s31, 0
	s_cmp_gt_u32 s44, 41
	s_mov_b64 s[22:23], s[24:25]
	s_cbranch_scc0 .LBB0_75
	s_branch .Lpeel_exit_2

; #define PG8_STAGE(bufoff, gbase, voff) do { _Pragma("unroll") for (int _i = 0; _i < 2; ++_i) \
;         __builtin_amdgcn_global_load_lds((const unsigned*)((const char*)(gbase) + (voff)[_i]), (PG8_LAS unsigned*)(lds + (bufoff) + ldsw + _i * 8192), 16, 0, 0); } while (0)
; #define PG8_LDA(dst, b, h) do { _Pragma("unroll") for (int m = 0; m < 4; ++m) _Pragma("unroll") for (int k = 0; k < 2; ++k) dst[m][k] = *(const PG8_LAS bf16x8*)(lds + PG8_SA(b, h) + aoff + m * 2048 + k * 1024); } while (0)
; #define PG8_LDB(dst, b, h) do { _Pragma("unroll") for (int n = 0; n < 2; ++n) _Pragma("unroll") for (int k = 0; k < 2; ++k) dst[n][k] = *(const PG8_LAS bf16x8*)(lds + PG8_SB(b, h) + boff + n * 2048 + k * 1024); } while (0)
; #define PG8_WAIT_V(n) asm volatile("s_waitcnt vmcnt(" #n ")" ::: "memory")
; #define PG8_WAIT_L(n) asm volatile("s_waitcnt lgkmcnt(" #n ")" ::: "memory")
; template <class Epi, class Sched, bool ALIGN_EPI = false, bool SP2 = false>
; __device__ __forceinline__ void gemm_phase(PG8_LAS unsigned char* lds, const Gemm g, const Sched& S, const Epi& E, int tid_in) {
;     ...
;         const char* nA = has_next ? g.apanel(nxt.pm, tstep) : cA; const char* nB = has_next ? (const char*)g.Bt + (size_t)nxt.pn * tstep : cB;
;         for (int seg = 0; seg < (Epi::KSEG ? 3 : 1); ++seg) {
;         if constexpr (Epi::KSEG) { if (seg > 0) E.kscale(acc, seg, cur, wr, fr); }
;         const int tb_ = Epi::KSEG ? (seg == 0 ? 0 : (seg == 1 ? 8 : 12)) : 0, te_ = Epi::KSEG ? (seg == 0 ? 8 : (seg == 1 ? 12 : nt)) : nt;
; #pragma unroll 1
;         for (int t = tb_; t < te_; t += 2) {
;             const bool last = (t == nt - 2);
;             const char* a1 = cA + (size_t)(t + 1) * kstep;
;             const char* a2 = last ? nA : cA + (size_t)(t + 2) * kstep; const char* b2 = last ? nB : cB + (size_t)(t + 2) * kstep;
;             const char* a3 = a2 + kstep; const char* b3 = b2 + kstep;
;             if (last && has_next) S.a_ready(nxt);
;             if constexpr (SP2) {
;             PG8_LDB(B0, 0, 0); PG8_LDB(B1, 0, 1); PG8_SCHED; PG8_LDA(At, 0, 0); PG8_STAGE(PG8_SA(1, 1), a1 + hstep, voffA);
;             PG8_WAIT_V(8); PG8_WAIT_L(0); PG8_BAR; PG8_MMA(0, 0, At, B0); PG8_MMA(0, 1, At, B1); PG8_BAR; PG8_SCHED;
;             PG8_LDA(At, 0, 1); PG8_STAGE(PG8_SB(0, 0), b2, voffB); PG8_STAGE(PG8_SB(0, 1), b2 + hstep, voffB); PG8_STAGE(PG8_SA(0, 0), a2, voffA);
.LBB0_241:
	s_ashr_i32 s51, s50, 31
	s_lshl_b64 s[30:31], s[50:51], 19
	s_add_u32 s56, s37, s30
	s_addc_u32 s57, s62, s31
	s_and_b64 s[30:31], s[40:41], exec
	s_cselect_b32 s23, s57, s27
	s_cselect_b32 s25, s56, s26
	s_ashr_i32 s49, s48, 31
	s_lshl_b64 s[30:31], s[48:49], 19
	s_add_u32 s60, s63, s30
	s_addc_u32 s61, s66, s31
	s_and_b64 s[30:31], s[40:41], exec
	s_cselect_b32 s34, s61, s29
	s_cselect_b32 s35, s60, s28
	s_add_u32 s26, s26, 0x40080
	s_addc_u32 s27, s27, 0
	s_add_u32 s42, s28, 0x100
	s_addc_u32 s43, s29, 0
	s_mov_b32 s44, -2
	s_add_u32 s28, s26, 0xfffc0080
	s_addc_u32 s29, s27, -1
	s_add_i32 s45, 0, 0x10000
	s_cmp_eq_u32 s44, 12
	s_cselect_b32 s31, s23, s29
	s_cselect_b32 s30, s25, s28
	v_add_u32_e32 v64, s45, v171
	s_cselect_b32 s29, s34, s43
	s_cselect_b32 s28, s35, s42
	s_add_i32 s49, 0, 0x14000
	ds_read_b128 v[122:125], v64
	ds_read_b128 v[126:129], v64 offset:1024
	ds_read_b128 v[130:133], v64 offset:2048
	ds_read_b128 v[134:137], v64 offset:3072
	v_add_u32_e32 v64, s49, v171
	ds_read_b128 v[146:149], v64
	ds_read_b128 v[150:153], v64 offset:1024
	ds_read_b128 v[154:157], v64 offset:2048
	ds_read_b128 v[158:161], v64 offset:3072
	s_add_i32 m0, s67, 0xc000
	ds_read_b128 v[162:165], v216
	ds_read_b128 v[166:169], v216 offset:1024
	ds_read_b128 v[192:195], v216 offset:2048
	ds_read_b128 v[196:199], v216 offset:3072
	ds_read_b128 v[200:203], v216 offset:4096
	ds_read_b128 v[204:207], v216 offset:5120
	ds_read_b128 v[208:211], v216 offset:6144
	ds_read_b128 v[212:215], v216 offset:7168
	global_load_lds_dwordx4 v188, s[26:27]
	s_add_i32 m0, s67, 0xe000
	s_nop 0
	global_load_lds_dwordx4 v190, s[26:27]
	s_waitcnt vmcnt(8)
	s_waitcnt lgkmcnt(0)
	s_barrier
	s_setprio 1
	s_waitcnt lgkmcnt(0)
	v_mfma_f32_16x16x32_bf16 v[114:117], v[122:125], v[162:165], 0
	v_mfma_f32_16x16x32_bf16 v[106:109], v[130:133], v[162:165], 0
	v_mfma_f32_16x16x32_bf16 v[142:145], v[122:125], v[192:195], 0
	v_mfma_f32_16x16x32_bf16 v[44:47], v[130:133], v[192:195], 0
	v_mfma_f32_16x16x32_bf16 v[110:113], v[122:125], v[200:203], 0
	v_mfma_f32_16x16x32_bf16 v[36:39], v[130:133], v[200:203], 0
	v_mfma_f32_16x16x32_bf16 v[118:121], v[122:125], v[208:211], 0
	v_mfma_f32_16x16x32_bf16 v[52:55], v[130:133], v[208:211], 0
	v_mfma_f32_16x16x32_bf16 v[114:117], v[126:129], v[166:169], v[114:117]
	v_mfma_f32_16x16x32_bf16 v[106:109], v[134:137], v[166:169], v[106:109]
	v_mfma_f32_16x16x32_bf16 v[142:145], v[126:129], v[196:199], v[142:145]
	v_mfma_f32_16x16x32_bf16 v[44:47], v[134:137], v[196:199], v[44:47]
	v_mfma_f32_16x16x32_bf16 v[110:113], v[126:129], v[204:207], v[110:113]
	v_mfma_f32_16x16x32_bf16 v[36:39], v[134:137], v[204:207], v[36:39]
	v_mfma_f32_16x16x32_bf16 v[118:121], v[126:129], v[212:215], v[118:121]
	v_mfma_f32_16x16x32_bf16 v[52:55], v[134:137], v[212:215], v[52:55]
	v_mfma_f32_16x16x32_bf16 v[102:105], v[146:149], v[162:165], 0
	v_mfma_f32_16x16x32_bf16 v[78:81], v[154:157], v[162:165], 0
	v_mfma_f32_16x16x32_bf16 v[138:141], v[146:149], v[192:195], 0
	v_mfma_f32_16x16x32_bf16 v[40:43], v[154:157], v[192:195], 0
	v_mfma_f32_16x16x32_bf16 v[98:101], v[146:149], v[200:203], 0
	v_mfma_f32_16x16x32_bf16 v[32:35], v[154:157], v[200:203], 0
	v_mfma_f32_16x16x32_bf16 v[94:97], v[146:149], v[208:211], 0
	v_mfma_f32_16x16x32_bf16 v[48:51], v[154:157], v[208:211], 0
	v_mfma_f32_16x16x32_bf16 v[102:105], v[150:153], v[166:169], v[102:105]
	v_mfma_f32_16x16x32_bf16 v[78:81], v[158:161], v[166:169], v[78:81]
	v_mfma_f32_16x16x32_bf16 v[138:141], v[150:153], v[196:199], v[138:141]
	v_mfma_f32_16x16x32_bf16 v[40:43], v[158:161], v[196:199], v[40:43]
	v_mfma_f32_16x16x32_bf16 v[98:101], v[150:153], v[204:207], v[98:101]
	v_mfma_f32_16x16x32_bf16 v[32:35], v[158:161], v[204:207], v[32:35]
	v_mfma_f32_16x16x32_bf16 v[94:97], v[150:153], v[212:215], v[94:97]
	v_mfma_f32_16x16x32_bf16 v[48:51], v[158:161], v[212:215], v[48:51]
	s_setprio 0
	s_barrier
	s_add_i32 s45, s45, s9
	v_lshl_add_u64 v[172:173], s[28:29], 0, v[178:179]
	s_mov_b32 m0, s45
	ds_read_b128 v[162:165], v216 offset:16384
	ds_read_b128 v[166:169], v216 offset:17408
	ds_read_b128 v[192:195], v216 offset:18432
	ds_read_b128 v[196:199], v216 offset:19456
	ds_read_b128 v[200:203], v216 offset:20480
	ds_read_b128 v[204:207], v216 offset:21504
	ds_read_b128 v[208:211], v216 offset:22528
	ds_read_b128 v[212:215], v216 offset:23552
	global_load_lds_dwordx4 v178, s[28:29]
	s_add_i32 m0, s45, 0x2000
	s_add_u32 s46, s28, 0x40000
	v_lshl_add_u64 v[220:221], s[28:29], 0, v[182:183]
	s_addc_u32 s47, s29, 0
	s_add_i32 s45, s49, s9
	global_load_lds_dwordx4 v182, s[28:29]
	s_mov_b32 m0, s45
	v_lshl_add_u64 v[224:225], s[30:31], 0, v[180:181]
	global_load_lds_dwordx4 v178, s[46:47]
	s_add_i32 m0, s45, 0x2000
	s_nop 0
	global_load_lds_dwordx4 v182, s[46:47]
	v_lshl_add_u64 v[222:223], s[30:31], 0, v[176:177]
	s_mov_b32 m0, s67
	s_nop 0
	global_load_lds_dwordx4 v176, s[30:31]
	s_mov_b32 m0, s69
	s_nop 0
	global_load_lds_dwordx4 v180, s[30:31]
	s_waitcnt vmcnt(8)
	s_waitcnt lgkmcnt(0)
	s_barrier
; #define PG8_STAGE(bufoff, gbase, voff) do { _Pragma("unroll") for (int _i = 0; _i < 2; ++_i) \
;         __builtin_amdgcn_global_load_lds((const unsigned*)((const char*)(gbase) + (voff)[_i]), (PG8_LAS unsigned*)(lds + (bufoff) + ldsw + _i * 8192), 16, 0, 0); } while (0)
; #define PG8_LDA(dst, b, h) do { _Pragma("unroll") for (int m = 0; m < 4; ++m) _Pragma("unroll") for (int k = 0; k < 2; ++k) dst[m][k] = *(const PG8_LAS bf16x8*)(lds + PG8_SA(b, h) + aoff + m * 2048 + k * 1024); } while (0)
; #define PG8_LDB(dst, b, h) do { _Pragma("unroll") for (int n = 0; n < 2; ++n) _Pragma("unroll") for (int k = 0; k < 2; ++k) dst[n][k] = *(const PG8_LAS bf16x8*)(lds + PG8_SB(b, h) + boff + n * 2048 + k * 1024); } while (0)
; #define PG8_MMA(ai, bj, At, Bt) do { __builtin_amdgcn_s_setprio(1); _Pragma("unroll") for (int m = 0; m < 4; ++m) _Pragma("unroll") for (int n = 0; n < 2; ++n) _Pragma("unroll") for (int k = 0; k < 2; ++k) \
;         acc[ai][bj][m][n] = __builtin_amdgcn_mfma_f32_16x16x32_bf16(Bt[n][k], At[m][k], acc[ai][bj][m][n], 0, 0, 0); __builtin_amdgcn_s_setprio(0); } while (0)
; #define PG8_WAIT_V(n) asm volatile("s_waitcnt vmcnt(" #n ")" ::: "memory")
; #define PG8_WAIT_L(n) asm volatile("s_waitcnt lgkmcnt(" #n ")" ::: "memory")
; #define PG8_BAR __builtin_amdgcn_s_barrier()
; #define PG8_SCHED __builtin_amdgcn_sched_barrier(0)
; template <class Epi, class Sched, bool ALIGN_EPI = false, bool SP2 = false>
; __device__ __forceinline__ void gemm_phase(PG8_LAS unsigned char* lds, const Gemm g, const Sched& S, const Epi& E, int tid_in) {
;     ...
;             PG8_WAIT_V(8); PG8_WAIT_L(0); PG8_BAR; PG8_MMA(1, 0, At, B0); PG8_MMA(1, 1, At, B1); PG8_BAR; PG8_SCHED;
;             PG8_LDB(B0, 1, 0); PG8_LDB(B1, 1, 1); PG8_SCHED; PG8_LDA(At, 1, 0); PG8_STAGE(PG8_SA(0, 1), a2 + hstep, voffA);
;             PG8_WAIT_V(8); PG8_WAIT_L(0); PG8_BAR; PG8_MMA(0, 0, At, B0); PG8_MMA(0, 1, At, B1); PG8_BAR; PG8_SCHED;
	s_setprio 1
	s_waitcnt lgkmcnt(0)
	v_mfma_f32_16x16x32_bf16 v[82:85], v[122:125], v[162:165], 0
	v_mfma_f32_16x16x32_bf16 v[20:23], v[130:133], v[162:165], 0
	v_mfma_f32_16x16x32_bf16 v[70:73], v[122:125], v[192:195], 0
	v_mfma_f32_16x16x32_bf16 v[12:15], v[130:133], v[192:195], 0
	v_mfma_f32_16x16x32_bf16 v[60:63], v[122:125], v[200:203], 0
	v_mfma_f32_16x16x32_bf16 v[4:7], v[130:133], v[200:203], 0
	v_mfma_f32_16x16x32_bf16 v[90:93], v[122:125], v[208:211], 0
	v_mfma_f32_16x16x32_bf16 v[28:31], v[130:133], v[208:211], 0
	v_mfma_f32_16x16x32_bf16 v[82:85], v[126:129], v[166:169], v[82:85]
	v_mfma_f32_16x16x32_bf16 v[20:23], v[134:137], v[166:169], v[20:23]
	v_mfma_f32_16x16x32_bf16 v[70:73], v[126:129], v[196:199], v[70:73]
	v_mfma_f32_16x16x32_bf16 v[12:15], v[134:137], v[196:199], v[12:15]
	v_mfma_f32_16x16x32_bf16 v[60:63], v[126:129], v[204:207], v[60:63]
	v_mfma_f32_16x16x32_bf16 v[4:7], v[134:137], v[204:207], v[4:7]
	v_mfma_f32_16x16x32_bf16 v[90:93], v[126:129], v[212:215], v[90:93]
	v_mfma_f32_16x16x32_bf16 v[28:31], v[134:137], v[212:215], v[28:31]
	v_mfma_f32_16x16x32_bf16 v[74:77], v[146:149], v[162:165], 0
	v_mfma_f32_16x16x32_bf16 v[16:19], v[154:157], v[162:165], 0
	v_mfma_f32_16x16x32_bf16 v[66:69], v[146:149], v[192:195], 0
	v_mfma_f32_16x16x32_bf16 v[8:11], v[154:157], v[192:195], 0
	v_mfma_f32_16x16x32_bf16 v[56:59], v[146:149], v[200:203], 0
	v_mfma_f32_16x16x32_bf16 v[0:3], v[154:157], v[200:203], 0
	v_mfma_f32_16x16x32_bf16 v[86:89], v[146:149], v[208:211], 0
	v_mfma_f32_16x16x32_bf16 v[24:27], v[154:157], v[208:211], 0
	v_mfma_f32_16x16x32_bf16 v[74:77], v[150:153], v[166:169], v[74:77]
	v_mfma_f32_16x16x32_bf16 v[16:19], v[158:161], v[166:169], v[16:19]
	v_mfma_f32_16x16x32_bf16 v[66:69], v[150:153], v[196:199], v[66:69]
	v_mfma_f32_16x16x32_bf16 v[8:11], v[158:161], v[196:199], v[8:11]
	v_mfma_f32_16x16x32_bf16 v[56:59], v[150:153], v[204:207], v[56:59]
	v_mfma_f32_16x16x32_bf16 v[0:3], v[158:161], v[204:207], v[0:3]
	v_mfma_f32_16x16x32_bf16 v[86:89], v[150:153], v[212:215], v[86:89]
	v_mfma_f32_16x16x32_bf16 v[24:27], v[158:161], v[212:215], v[24:27]
	s_setprio 0
	s_barrier
	s_add_i32 s45, 0, 0x18000
	v_add_u32_e32 v64, s45, v171
	s_add_i32 s46, 0, 0x1c000
	ds_read_b128 v[122:125], v64
	ds_read_b128 v[126:129], v64 offset:1024
	ds_read_b128 v[130:133], v64 offset:2048
	ds_read_b128 v[134:137], v64 offset:3072
	v_add_u32_e32 v64, s46, v171
	ds_read_b128 v[146:149], v64
	ds_read_b128 v[150:153], v64 offset:1024
	ds_read_b128 v[154:157], v64 offset:2048
	ds_read_b128 v[158:161], v64 offset:3072
	s_add_u32 s30, s30, 0x40000
	s_addc_u32 s31, s31, 0
	s_mov_b32 m0, s79
	ds_read_b128 v[162:165], v216 offset:32768
	ds_read_b128 v[166:169], v216 offset:33792
	ds_read_b128 v[192:195], v216 offset:34816
	ds_read_b128 v[196:199], v216 offset:35840
	ds_read_b128 v[200:203], v216 offset:36864
	ds_read_b128 v[204:207], v216 offset:37888
	ds_read_b128 v[208:211], v216 offset:38912
	ds_read_b128 v[212:215], v216 offset:39936
	global_load_lds_dwordx4 v176, s[30:31]
	s_mov_b32 m0, s82
	s_nop 0
	global_load_lds_dwordx4 v180, s[30:31]
	s_waitcnt vmcnt(8)
	s_waitcnt lgkmcnt(0)
	s_barrier
	s_setprio 1
	s_waitcnt lgkmcnt(0)
	v_mfma_f32_16x16x32_bf16 v[114:117], v[122:125], v[162:165], v[114:117]
	v_mfma_f32_16x16x32_bf16 v[106:109], v[130:133], v[162:165], v[106:109]
	v_mfma_f32_16x16x32_bf16 v[142:145], v[122:125], v[192:195], v[142:145]
	v_mfma_f32_16x16x32_bf16 v[44:47], v[130:133], v[192:195], v[44:47]
	v_mfma_f32_16x16x32_bf16 v[110:113], v[122:125], v[200:203], v[110:113]
	v_mfma_f32_16x16x32_bf16 v[36:39], v[130:133], v[200:203], v[36:39]
	v_mfma_f32_16x16x32_bf16 v[118:121], v[122:125], v[208:211], v[118:121]
	v_mfma_f32_16x16x32_bf16 v[52:55], v[130:133], v[208:211], v[52:55]
	v_mfma_f32_16x16x32_bf16 v[114:117], v[126:129], v[166:169], v[114:117]
	v_mfma_f32_16x16x32_bf16 v[106:109], v[134:137], v[166:169], v[106:109]
	v_mfma_f32_16x16x32_bf16 v[142:145], v[126:129], v[196:199], v[142:145]
	v_mfma_f32_16x16x32_bf16 v[44:47], v[134:137], v[196:199], v[44:47]
	v_mfma_f32_16x16x32_bf16 v[110:113], v[126:129], v[204:207], v[110:113]
	v_mfma_f32_16x16x32_bf16 v[36:39], v[134:137], v[204:207], v[36:39]
	v_mfma_f32_16x16x32_bf16 v[118:121], v[126:129], v[212:215], v[118:121]
	v_mfma_f32_16x16x32_bf16 v[52:55], v[134:137], v[212:215], v[52:55]
	v_mfma_f32_16x16x32_bf16 v[102:105], v[146:149], v[162:165], v[102:105]
	v_mfma_f32_16x16x32_bf16 v[78:81], v[154:157], v[162:165], v[78:81]
	v_mfma_f32_16x16x32_bf16 v[138:141], v[146:149], v[192:195], v[138:141]
	v_mfma_f32_16x16x32_bf16 v[40:43], v[154:157], v[192:195], v[40:43]
	v_mfma_f32_16x16x32_bf16 v[98:101], v[146:149], v[200:203], v[98:101]
	v_mfma_f32_16x16x32_bf16 v[32:35], v[154:157], v[200:203], v[32:35]
	v_mfma_f32_16x16x32_bf16 v[94:97], v[146:149], v[208:211], v[94:97]
	v_mfma_f32_16x16x32_bf16 v[48:51], v[154:157], v[208:211], v[48:51]
	v_mfma_f32_16x16x32_bf16 v[102:105], v[150:153], v[166:169], v[102:105]
	v_mfma_f32_16x16x32_bf16 v[78:81], v[158:161], v[166:169], v[78:81]
	v_mfma_f32_16x16x32_bf16 v[138:141], v[150:153], v[196:199], v[138:141]
	v_mfma_f32_16x16x32_bf16 v[40:43], v[158:161], v[196:199], v[40:43]
	v_mfma_f32_16x16x32_bf16 v[98:101], v[150:153], v[204:207], v[98:101]
	v_mfma_f32_16x16x32_bf16 v[32:35], v[158:161], v[204:207], v[32:35]
	v_mfma_f32_16x16x32_bf16 v[94:97], v[150:153], v[212:215], v[94:97]
	v_mfma_f32_16x16x32_bf16 v[48:51], v[158:161], v[212:215], v[48:51]
	s_setprio 0
	s_barrier
; #define PG8_STAGE(bufoff, gbase, voff) do { _Pragma("unroll") for (int _i = 0; _i < 2; ++_i) \
;         __builtin_amdgcn_global_load_lds((const unsigned*)((const char*)(gbase) + (voff)[_i]), (PG8_LAS unsigned*)(lds + (bufoff) + ldsw + _i * 8192), 16, 0, 0); } while (0)
; #define PG8_LDA(dst, b, h) do { _Pragma("unroll") for (int m = 0; m < 4; ++m) _Pragma("unroll") for (int k = 0; k < 2; ++k) dst[m][k] = *(const PG8_LAS bf16x8*)(lds + PG8_SA(b, h) + aoff + m * 2048 + k * 1024); } while (0)
; #define PG8_MMA(ai, bj, At, Bt) do { __builtin_amdgcn_s_setprio(1); _Pragma("unroll") for (int m = 0; m < 4; ++m) _Pragma("unroll") for (int n = 0; n < 2; ++n) _Pragma("unroll") for (int k = 0; k < 2; ++k) \
;         acc[ai][bj][m][n] = __builtin_amdgcn_mfma_f32_16x16x32_bf16(Bt[n][k], At[m][k], acc[ai][bj][m][n], 0, 0, 0); __builtin_amdgcn_s_setprio(0); } while (0)
; #define PG8_WAIT_V(n) asm volatile("s_waitcnt vmcnt(" #n ")" ::: "memory")
; #define PG8_WAIT_L(n) asm volatile("s_waitcnt lgkmcnt(" #n ")" ::: "memory")
; #define PG8_BAR __builtin_amdgcn_s_barrier()
; #define PG8_SCHED __builtin_amdgcn_sched_barrier(0)
; template <class Epi, class Sched, bool ALIGN_EPI = false, bool SP2 = false>
; __device__ __forceinline__ void gemm_phase(PG8_LAS unsigned char* lds, const Gemm g, const Sched& S, const Epi& E, int tid_in) {
;     ...
;             PG8_LDA(At, 1, 1); PG8_STAGE(PG8_SB(1, 0), b3, voffB); PG8_STAGE(PG8_SB(1, 1), b3 + hstep, voffB); PG8_STAGE(PG8_SA(1, 0), a3, voffA);
;             PG8_WAIT_V(8); PG8_WAIT_L(0); PG8_BAR; PG8_MMA(1, 0, At, B0); PG8_MMA(1, 1, At, B1); PG8_BAR; PG8_SCHED;
	s_add_i32 s30, s45, s9
	s_mov_b32 m0, s30
	ds_read_b128 v[162:165], v216 offset:49152
	ds_read_b128 v[166:169], v216 offset:50176
	ds_read_b128 v[192:195], v216 offset:51200
	ds_read_b128 v[196:199], v216 offset:52224
	ds_read_b128 v[200:203], v216 offset:53248
	ds_read_b128 v[204:207], v216 offset:54272
	ds_read_b128 v[208:211], v216 offset:55296
	ds_read_b128 v[212:215], v216 offset:56320
	s_add_u32 s98, s28, 0x80
	s_addc_u32 s99, s29, 0
	global_load_lds_dwordx4 v178, s[98:99]
	s_add_i32 m0, s30, 0x2000
	s_add_u32 s28, s28, 0x40080
	v_lshl_add_u64 v[172:173], v[220:221], 0, s[92:93]
	s_addc_u32 s29, s29, 0
	s_add_i32 s30, s46, s9
	global_load_lds_dwordx4 v[172:173], off
	s_mov_b32 m0, s30
	s_nop 0
	global_load_lds_dwordx4 v178, s[28:29]
	s_add_i32 m0, s30, 0x2000
	s_nop 0
	global_load_lds_dwordx4 v182, s[28:29]
	v_lshl_add_u64 v[172:173], v[222:223], 0, s[92:93]
	s_mov_b32 m0, s85
	s_nop 0
	global_load_lds_dwordx4 v[172:173], off
	v_lshl_add_u64 v[172:173], v[224:225], 0, s[92:93]
	s_mov_b32 m0, s8
	s_nop 0
	global_load_lds_dwordx4 v[172:173], off
	s_waitcnt vmcnt(8)
	s_waitcnt lgkmcnt(0)
	s_barrier
	s_setprio 1
	s_waitcnt lgkmcnt(0)
	v_mfma_f32_16x16x32_bf16 v[82:85], v[122:125], v[162:165], v[82:85]
	v_mfma_f32_16x16x32_bf16 v[20:23], v[130:133], v[162:165], v[20:23]
	v_mfma_f32_16x16x32_bf16 v[70:73], v[122:125], v[192:195], v[70:73]
	v_mfma_f32_16x16x32_bf16 v[12:15], v[130:133], v[192:195], v[12:15]
	v_mfma_f32_16x16x32_bf16 v[60:63], v[122:125], v[200:203], v[60:63]
	v_mfma_f32_16x16x32_bf16 v[4:7], v[130:133], v[200:203], v[4:7]
	v_mfma_f32_16x16x32_bf16 v[90:93], v[122:125], v[208:211], v[90:93]
	v_mfma_f32_16x16x32_bf16 v[28:31], v[130:133], v[208:211], v[28:31]
	v_mfma_f32_16x16x32_bf16 v[82:85], v[126:129], v[166:169], v[82:85]
	v_mfma_f32_16x16x32_bf16 v[20:23], v[134:137], v[166:169], v[20:23]
	v_mfma_f32_16x16x32_bf16 v[70:73], v[126:129], v[196:199], v[70:73]
	v_mfma_f32_16x16x32_bf16 v[12:15], v[134:137], v[196:199], v[12:15]
	v_mfma_f32_16x16x32_bf16 v[60:63], v[126:129], v[204:207], v[60:63]
	v_mfma_f32_16x16x32_bf16 v[4:7], v[134:137], v[204:207], v[4:7]
	v_mfma_f32_16x16x32_bf16 v[90:93], v[126:129], v[212:215], v[90:93]
	v_mfma_f32_16x16x32_bf16 v[28:31], v[134:137], v[212:215], v[28:31]
	v_mfma_f32_16x16x32_bf16 v[74:77], v[146:149], v[162:165], v[74:77]
	v_mfma_f32_16x16x32_bf16 v[16:19], v[154:157], v[162:165], v[16:19]
	v_mfma_f32_16x16x32_bf16 v[66:69], v[146:149], v[192:195], v[66:69]
	v_mfma_f32_16x16x32_bf16 v[8:11], v[154:157], v[192:195], v[8:11]
	v_mfma_f32_16x16x32_bf16 v[56:59], v[146:149], v[200:203], v[56:59]
	v_mfma_f32_16x16x32_bf16 v[0:3], v[154:157], v[200:203], v[0:3]
	v_mfma_f32_16x16x32_bf16 v[86:89], v[146:149], v[208:211], v[86:89]
	v_mfma_f32_16x16x32_bf16 v[24:27], v[154:157], v[208:211], v[24:27]
	v_mfma_f32_16x16x32_bf16 v[74:77], v[150:153], v[166:169], v[74:77]
	v_mfma_f32_16x16x32_bf16 v[16:19], v[158:161], v[166:169], v[16:19]
	v_mfma_f32_16x16x32_bf16 v[66:69], v[150:153], v[196:199], v[66:69]
	v_mfma_f32_16x16x32_bf16 v[8:11], v[158:161], v[196:199], v[8:11]
	v_mfma_f32_16x16x32_bf16 v[56:59], v[150:153], v[204:207], v[56:59]
	v_mfma_f32_16x16x32_bf16 v[0:3], v[158:161], v[204:207], v[0:3]
	v_mfma_f32_16x16x32_bf16 v[86:89], v[150:153], v[212:215], v[86:89]
	v_mfma_f32_16x16x32_bf16 v[24:27], v[158:161], v[212:215], v[24:27]
	s_setprio 0
	s_barrier
	s_add_i32 s44, s44, 2
	s_add_u32 s26, s26, 0x100
	s_addc_u32 s27, s27, 0
	s_add_u32 s42, s42, 0x100
	s_addc_u32 s43, s43, 0
	s_cmp_gt_u32 s44, 13
	s_cbranch_scc0 .LBB0_242
	s_branch .Lpeel_exit_1

; #define PG8_STAGE(bufoff, gbase, voff) do { _Pragma("unroll") for (int _i = 0; _i < 2; ++_i) \
;         __builtin_amdgcn_global_load_lds((const unsigned*)((const char*)(gbase) + (voff)[_i]), (PG8_LAS unsigned*)(lds + (bufoff) + ldsw + _i * 8192), 16, 0, 0); } while (0)
; #define PG8_LDA(dst, b, h) do { _Pragma("unroll") for (int m = 0; m < 4; ++m) _Pragma("unroll") for (int k = 0; k < 2; ++k) dst[m][k] = *(const PG8_LAS bf16x8*)(lds + PG8_SA(b, h) + aoff + m * 2048 + k * 1024); } while (0)
; #define PG8_WAIT_V(n) asm volatile("s_waitcnt vmcnt(" #n ")" ::: "memory")
; #define PG8_WAIT_L(n) asm volatile("s_waitcnt lgkmcnt(" #n ")" ::: "memory")
; template <class Epi, class Sched, bool ALIGN_EPI = false, bool SP2 = false>
; __device__ __forceinline__ void gemm_phase(PG8_LAS unsigned char* lds, const Gemm g, const Sched& S, const Epi& E, int tid_in) {
;     ...
;         const char* nA = has_next ? g.apanel(nxt.pm, tstep) : cA; const char* nB = has_next ? (const char*)g.Bt + (size_t)nxt.pn * tstep : cB;
;         for (int seg = 0; seg < (Epi::KSEG ? 3 : 1); ++seg) {
;         if constexpr (Epi::KSEG) { if (seg > 0) E.kscale(acc, seg, cur, wr, fr); }
;         const int tb_ = Epi::KSEG ? (seg == 0 ? 0 : (seg == 1 ? 8 : 12)) : 0, te_ = Epi::KSEG ? (seg == 0 ? 8 : (seg == 1 ? 12 : nt)) : nt;
; #pragma unroll 1
;         for (int t = tb_; t < te_; t += 2) {
;             const bool last = (t == nt - 2);
;             const char* a1 = cA + (size_t)(t + 1) * kstep;
;             const char* a2 = last ? nA : cA + (size_t)(t + 2) * kstep; const char* b2 = last ? nB : cB + (size_t)(t + 2) * kstep;
;             const char* a3 = a2 + kstep; const char* b3 = b2 + kstep;
;             if (last && has_next) S.a_ready(nxt);
;             if constexpr (SP2) {
;             PG8_LDB(B0, 0, 0); PG8_LDB(B1, 0, 1); PG8_SCHED; PG8_LDA(At, 0, 0); PG8_STAGE(PG8_SA(1, 1), a1 + hstep, voffA);
;             PG8_WAIT_V(8); PG8_WAIT_L(0); PG8_BAR; PG8_MMA(0, 0, At, B0); PG8_MMA(0, 1, At, B1); PG8_BAR; PG8_SCHED;
;             PG8_LDA(At, 0, 1); PG8_STAGE(PG8_SB(0, 0), b2, voffB); PG8_STAGE(PG8_SB(0, 1), b2 + hstep, voffB); PG8_STAGE(PG8_SA(0, 0), a2, voffA);
;     DI void operator()(const pg8::f32x4 (&acc)[2][2][4][2], const pg8::Unit& u, int wr, int wc, int fr, int fq) const {
;     ...
;                 const int row = u.pm * 256 + ai * 128 + wr * 64 + m * 16 + fr; const float rs = rstdx[row];
.LBB0_753:
	s_ashr_i32 s19, s18, 31
	s_lshl_b64 s[20:21], s[18:19], 19
	s_add_u32 s20, s7, s20
	s_addc_u32 s21, s34, s21
	s_and_b64 s[22:23], s[38:39], exec
	s_cselect_b32 s19, s21, s27
	s_cselect_b32 s44, s20, s26
	s_ashr_i32 s17, s16, 31
	s_lshl_b64 s[22:23], s[16:17], 19
	v_readlane_b32 s30, v255, 3
	v_readlane_b32 s31, v255, 4
	s_add_u32 s22, s30, s22
	s_addc_u32 s23, s31, s23
	s_and_b64 s[30:31], s[38:39], exec
	s_cselect_b32 s17, s23, s29
	s_cselect_b32 s45, s22, s28
	s_add_u32 s26, s26, 0x40080
	s_addc_u32 s27, s27, 0
	s_add_u32 s46, s28, 0x100
	s_addc_u32 s47, s29, 0
	s_mov_b32 s48, -2
	s_lshl_b32 s100, s24, 8
	v_add_u32_e32 v173, s100, v144
	v_mov_b32_e32 v250, v173
	v_ashrrev_i32_e32 v251, 31, v250
	v_lshl_add_u64 v[250:251], v[250:251], 2, s[8:9]
	global_load_dword v174, v[250:251], off
	v_add_u32_e32 v232, s100, v146
	v_ashrrev_i32_e32 v233, 31, v232
	v_lshl_add_u64 v[232:233], v[232:233], 2, s[8:9]
	global_load_dword v232, v[232:233], off
	v_add_u32_e32 v238, s100, v147
	v_ashrrev_i32_e32 v239, 31, v238
	v_lshl_add_u64 v[238:239], v[238:239], 2, s[8:9]
	global_load_dword v238, v[238:239], off
	v_add_u32_e32 v242, s100, v148
	v_ashrrev_i32_e32 v243, 31, v242
	v_lshl_add_u64 v[242:243], v[242:243], 2, s[8:9]
	global_load_dword v242, v[242:243], off
	v_add_u32_e32 v244, 0x80, v173
	v_ashrrev_i32_e32 v245, 31, v244
	v_lshl_add_u64 v[244:245], v[244:245], 2, s[8:9]
	global_load_dword v244, v[244:245], off
	v_add_u32_e32 v246, 0x90, v173
	v_ashrrev_i32_e32 v247, 31, v246
	v_lshl_add_u64 v[246:247], v[246:247], 2, s[8:9]
	global_load_dword v246, v[246:247], off
	v_add_u32_e32 v248, 0xa0, v173
	v_ashrrev_i32_e32 v249, 31, v248
	v_lshl_add_u64 v[248:249], v[248:249], 2, s[8:9]
	global_load_dword v248, v[248:249], off
	v_add_u32_e32 v250, 0xb0, v173
	v_ashrrev_i32_e32 v251, 31, v250
	v_lshl_add_u64 v[250:251], v[250:251], 2, s[8:9]
	global_load_dword v250, v[250:251], off
	s_add_u32 s28, s26, 0xfffc0080
	s_addc_u32 s29, s27, -1
	s_add_i32 s49, 0, 0x10000
	s_cmp_eq_u32 s48, 12
	s_cselect_b32 s31, s19, s29
	s_cselect_b32 s30, s44, s28
	v_add_u32_e32 v142, s49, v145
	s_cselect_b32 s29, s17, s47
	s_cselect_b32 s28, s45, s46
	s_add_i32 s52, 0, 0x14000
	ds_read_b128 v[150:153], v142
	ds_read_b128 v[154:157], v142 offset:1024
	ds_read_b128 v[158:161], v142 offset:2048
	ds_read_b128 v[162:165], v142 offset:3072
	v_add_u32_e32 v142, s52, v145
	ds_read_b128 v[166:169], v142
	ds_read_b128 v[176:179], v142 offset:1024
	ds_read_b128 v[180:183], v142 offset:2048
	ds_read_b128 v[184:187], v142 offset:3072
	s_add_i32 m0, s35, 0xc000
	ds_read_b128 v[188:191], v149
	ds_read_b128 v[192:195], v149 offset:1024
	ds_read_b128 v[196:199], v149 offset:2048
	ds_read_b128 v[200:203], v149 offset:3072
	ds_read_b128 v[204:207], v149 offset:4096
	ds_read_b128 v[208:211], v149 offset:5120
	ds_read_b128 v[212:215], v149 offset:6144
	ds_read_b128 v[216:219], v149 offset:7168
	global_load_lds_dwordx4 v138, s[26:27]
	s_add_i32 m0, s35, 0xe000
	s_nop 0
	global_load_lds_dwordx4 v140, s[26:27]
	s_waitcnt vmcnt(8)
	s_waitcnt lgkmcnt(0)
	s_barrier
	s_setprio 1
	s_waitcnt lgkmcnt(0)
	v_mfma_f32_16x16x32_bf16 v[126:129], v[150:153], v[188:191], 0
	v_mfma_f32_16x16x32_bf16 v[122:125], v[158:161], v[188:191], 0
	v_mfma_f32_16x16x32_bf16 v[110:113], v[150:153], v[196:199], 0
	v_mfma_f32_16x16x32_bf16 v[106:109], v[158:161], v[196:199], 0
	v_mfma_f32_16x16x32_bf16 v[94:97], v[150:153], v[204:207], 0
	v_mfma_f32_16x16x32_bf16 v[90:93], v[158:161], v[204:207], 0
	v_mfma_f32_16x16x32_bf16 v[78:81], v[150:153], v[212:215], 0
	v_mfma_f32_16x16x32_bf16 v[74:77], v[158:161], v[212:215], 0
	v_mfma_f32_16x16x32_bf16 v[126:129], v[154:157], v[192:195], v[126:129]
	v_mfma_f32_16x16x32_bf16 v[122:125], v[162:165], v[192:195], v[122:125]
	v_mfma_f32_16x16x32_bf16 v[110:113], v[154:157], v[200:203], v[110:113]
	v_mfma_f32_16x16x32_bf16 v[106:109], v[162:165], v[200:203], v[106:109]
	v_mfma_f32_16x16x32_bf16 v[94:97], v[154:157], v[208:211], v[94:97]
	v_mfma_f32_16x16x32_bf16 v[90:93], v[162:165], v[208:211], v[90:93]
	v_mfma_f32_16x16x32_bf16 v[78:81], v[154:157], v[216:219], v[78:81]
	v_mfma_f32_16x16x32_bf16 v[74:77], v[162:165], v[216:219], v[74:77]
	v_mfma_f32_16x16x32_bf16 v[118:121], v[166:169], v[188:191], 0
	v_mfma_f32_16x16x32_bf16 v[114:117], v[180:183], v[188:191], 0
	v_mfma_f32_16x16x32_bf16 v[102:105], v[166:169], v[196:199], 0
	v_mfma_f32_16x16x32_bf16 v[98:101], v[180:183], v[196:199], 0
	v_mfma_f32_16x16x32_bf16 v[86:89], v[166:169], v[204:207], 0
	v_mfma_f32_16x16x32_bf16 v[82:85], v[180:183], v[204:207], 0
	v_mfma_f32_16x16x32_bf16 v[70:73], v[166:169], v[212:215], 0
	v_mfma_f32_16x16x32_bf16 v[66:69], v[180:183], v[212:215], 0
	v_mfma_f32_16x16x32_bf16 v[118:121], v[176:179], v[192:195], v[118:121]
	v_mfma_f32_16x16x32_bf16 v[114:117], v[184:187], v[192:195], v[114:117]
	v_mfma_f32_16x16x32_bf16 v[102:105], v[176:179], v[200:203], v[102:105]
	v_mfma_f32_16x16x32_bf16 v[98:101], v[184:187], v[200:203], v[98:101]
	v_mfma_f32_16x16x32_bf16 v[86:89], v[176:179], v[208:211], v[86:89]
	v_mfma_f32_16x16x32_bf16 v[82:85], v[184:187], v[208:211], v[82:85]
	v_mfma_f32_16x16x32_bf16 v[70:73], v[176:179], v[216:219], v[70:73]
	v_mfma_f32_16x16x32_bf16 v[66:69], v[184:187], v[216:219], v[66:69]
	s_setprio 0
	s_barrier
; #define PG8_STAGE(bufoff, gbase, voff) do { _Pragma("unroll") for (int _i = 0; _i < 2; ++_i) \
;         __builtin_amdgcn_global_load_lds((const unsigned*)((const char*)(gbase) + (voff)[_i]), (PG8_LAS unsigned*)(lds + (bufoff) + ldsw + _i * 8192), 16, 0, 0); } while (0)
; #define PG8_LDA(dst, b, h) do { _Pragma("unroll") for (int m = 0; m < 4; ++m) _Pragma("unroll") for (int k = 0; k < 2; ++k) dst[m][k] = *(const PG8_LAS bf16x8*)(lds + PG8_SA(b, h) + aoff + m * 2048 + k * 1024); } while (0)
; #define PG8_LDB(dst, b, h) do { _Pragma("unroll") for (int n = 0; n < 2; ++n) _Pragma("unroll") for (int k = 0; k < 2; ++k) dst[n][k] = *(const PG8_LAS bf16x8*)(lds + PG8_SB(b, h) + boff + n * 2048 + k * 1024); } while (0)
; #define PG8_MMA(ai, bj, At, Bt) do { __builtin_amdgcn_s_setprio(1); _Pragma("unroll") for (int m = 0; m < 4; ++m) _Pragma("unroll") for (int n = 0; n < 2; ++n) _Pragma("unroll") for (int k = 0; k < 2; ++k) \
;         acc[ai][bj][m][n] = __builtin_amdgcn_mfma_f32_16x16x32_bf16(Bt[n][k], At[m][k], acc[ai][bj][m][n], 0, 0, 0); __builtin_amdgcn_s_setprio(0); } while (0)
; #define PG8_WAIT_V(n) asm volatile("s_waitcnt vmcnt(" #n ")" ::: "memory")
; #define PG8_WAIT_L(n) asm volatile("s_waitcnt lgkmcnt(" #n ")" ::: "memory")
; #define PG8_BAR __builtin_amdgcn_s_barrier()
; #define PG8_SCHED __builtin_amdgcn_sched_barrier(0)
; template <class Epi, class Sched, bool ALIGN_EPI = false, bool SP2 = false>
; __device__ __forceinline__ void gemm_phase(PG8_LAS unsigned char* lds, const Gemm g, const Sched& S, const Epi& E, int tid_in) {
;     ...
;             PG8_LDA(At, 0, 1); PG8_STAGE(PG8_SB(0, 0), b2, voffB); PG8_STAGE(PG8_SB(0, 1), b2 + hstep, voffB); PG8_STAGE(PG8_SA(0, 0), a2, voffA);
;             PG8_WAIT_V(8); PG8_WAIT_L(0); PG8_BAR; PG8_MMA(1, 0, At, B0); PG8_MMA(1, 1, At, B1); PG8_BAR; PG8_SCHED;
;             PG8_LDB(B0, 1, 0); PG8_LDB(B1, 1, 1); PG8_SCHED; PG8_LDA(At, 1, 0); PG8_STAGE(PG8_SA(0, 1), a2 + hstep, voffA);
	s_add_i32 s49, s49, s6
	v_lshl_add_u64 v[142:143], s[28:29], 0, v[132:133]
	s_mov_b32 m0, s49
	ds_read_b128 v[188:191], v149 offset:16384
	ds_read_b128 v[192:195], v149 offset:17408
	ds_read_b128 v[196:199], v149 offset:18432
	ds_read_b128 v[200:203], v149 offset:19456
	ds_read_b128 v[204:207], v149 offset:20480
	ds_read_b128 v[208:211], v149 offset:21504
	ds_read_b128 v[212:215], v149 offset:22528
	ds_read_b128 v[216:219], v149 offset:23552
	global_load_lds_dwordx4 v132, s[28:29]
	s_add_i32 m0, s49, 0x2000
	s_add_u32 s50, s28, 0x40000
	v_lshl_add_u64 v[170:171], s[28:29], 0, v[136:137]
	s_addc_u32 s51, s29, 0
	s_add_i32 s49, s52, s6
	global_load_lds_dwordx4 v136, s[28:29]
	s_mov_b32 m0, s49
	v_lshl_add_u64 v[222:223], s[30:31], 0, v[134:135]
	global_load_lds_dwordx4 v132, s[50:51]
	s_add_i32 m0, s49, 0x2000
	s_nop 0
	global_load_lds_dwordx4 v136, s[50:51]
	v_lshl_add_u64 v[220:221], s[30:31], 0, v[130:131]
	s_mov_b32 m0, s35
	s_nop 0
	global_load_lds_dwordx4 v130, s[30:31]
	s_mov_b32 m0, s36
	s_nop 0
	global_load_lds_dwordx4 v134, s[30:31]
	s_waitcnt vmcnt(8)
	s_waitcnt lgkmcnt(0)
	s_barrier
	s_setprio 1
	s_waitcnt lgkmcnt(0)
	v_mfma_f32_16x16x32_bf16 v[60:63], v[150:153], v[188:191], 0
	v_mfma_f32_16x16x32_bf16 v[56:59], v[158:161], v[188:191], 0
	v_mfma_f32_16x16x32_bf16 v[44:47], v[150:153], v[196:199], 0
	v_mfma_f32_16x16x32_bf16 v[40:43], v[158:161], v[196:199], 0
	v_mfma_f32_16x16x32_bf16 v[28:31], v[150:153], v[204:207], 0
	v_mfma_f32_16x16x32_bf16 v[24:27], v[158:161], v[204:207], 0
	v_mfma_f32_16x16x32_bf16 v[12:15], v[150:153], v[212:215], 0
	v_mfma_f32_16x16x32_bf16 v[8:11], v[158:161], v[212:215], 0
	v_mfma_f32_16x16x32_bf16 v[60:63], v[154:157], v[192:195], v[60:63]
	v_mfma_f32_16x16x32_bf16 v[56:59], v[162:165], v[192:195], v[56:59]
	v_mfma_f32_16x16x32_bf16 v[44:47], v[154:157], v[200:203], v[44:47]
	v_mfma_f32_16x16x32_bf16 v[40:43], v[162:165], v[200:203], v[40:43]
	v_mfma_f32_16x16x32_bf16 v[28:31], v[154:157], v[208:211], v[28:31]
	v_mfma_f32_16x16x32_bf16 v[24:27], v[162:165], v[208:211], v[24:27]
	v_mfma_f32_16x16x32_bf16 v[12:15], v[154:157], v[216:219], v[12:15]
	v_mfma_f32_16x16x32_bf16 v[8:11], v[162:165], v[216:219], v[8:11]
	v_mfma_f32_16x16x32_bf16 v[52:55], v[166:169], v[188:191], 0
	v_mfma_f32_16x16x32_bf16 v[48:51], v[180:183], v[188:191], 0
	v_mfma_f32_16x16x32_bf16 v[36:39], v[166:169], v[196:199], 0
	v_mfma_f32_16x16x32_bf16 v[32:35], v[180:183], v[196:199], 0
	v_mfma_f32_16x16x32_bf16 v[20:23], v[166:169], v[204:207], 0
	v_mfma_f32_16x16x32_bf16 v[16:19], v[180:183], v[204:207], 0
	v_mfma_f32_16x16x32_bf16 v[4:7], v[166:169], v[212:215], 0
	v_mfma_f32_16x16x32_bf16 v[0:3], v[180:183], v[212:215], 0
	v_mfma_f32_16x16x32_bf16 v[52:55], v[176:179], v[192:195], v[52:55]
	v_mfma_f32_16x16x32_bf16 v[48:51], v[184:187], v[192:195], v[48:51]
	v_mfma_f32_16x16x32_bf16 v[36:39], v[176:179], v[200:203], v[36:39]
	v_mfma_f32_16x16x32_bf16 v[32:35], v[184:187], v[200:203], v[32:35]
	v_mfma_f32_16x16x32_bf16 v[20:23], v[176:179], v[208:211], v[20:23]
	v_mfma_f32_16x16x32_bf16 v[16:19], v[184:187], v[208:211], v[16:19]
	v_mfma_f32_16x16x32_bf16 v[4:7], v[176:179], v[216:219], v[4:7]
	v_mfma_f32_16x16x32_bf16 v[0:3], v[184:187], v[216:219], v[0:3]
	s_setprio 0
	s_barrier
	s_add_i32 s49, 0, 0x18000
	s_add_i32 s50, 0, 0x1c000
	v_add_u32_e32 v162, s49, v145
	v_add_u32_e32 v172, s50, v145
	ds_read_b128 v[150:153], v162
	ds_read_b128 v[154:157], v162 offset:1024
	ds_read_b128 v[158:161], v162 offset:2048
	ds_read_b128 v[162:165], v162 offset:3072
	ds_read_b128 v[166:169], v172
	ds_read_b128 v[176:179], v172 offset:1024
	ds_read_b128 v[180:183], v172 offset:2048
	ds_read_b128 v[184:187], v172 offset:3072
	s_add_u32 s30, s30, 0x40000
	s_addc_u32 s31, s31, 0
	s_mov_b32 m0, s37
	ds_read_b128 v[188:191], v149 offset:32768
	ds_read_b128 v[192:195], v149 offset:33792
	ds_read_b128 v[196:199], v149 offset:34816
	ds_read_b128 v[200:203], v149 offset:35840
	ds_read_b128 v[204:207], v149 offset:36864
	ds_read_b128 v[208:211], v149 offset:37888
	ds_read_b128 v[212:215], v149 offset:38912
	ds_read_b128 v[216:219], v149 offset:39936
	global_load_lds_dwordx4 v130, s[30:31]
	s_mov_b32 m0, s40
	s_nop 0
	global_load_lds_dwordx4 v134, s[30:31]
	s_waitcnt vmcnt(8)
	s_waitcnt lgkmcnt(0)
	s_barrier
; #define PG8_STAGE(bufoff, gbase, voff) do { _Pragma("unroll") for (int _i = 0; _i < 2; ++_i) \
;         __builtin_amdgcn_global_load_lds((const unsigned*)((const char*)(gbase) + (voff)[_i]), (PG8_LAS unsigned*)(lds + (bufoff) + ldsw + _i * 8192), 16, 0, 0); } while (0)
; #define PG8_LDA(dst, b, h) do { _Pragma("unroll") for (int m = 0; m < 4; ++m) _Pragma("unroll") for (int k = 0; k < 2; ++k) dst[m][k] = *(const PG8_LAS bf16x8*)(lds + PG8_SA(b, h) + aoff + m * 2048 + k * 1024); } while (0)
; #define PG8_LDB(dst, b, h) do { _Pragma("unroll") for (int n = 0; n < 2; ++n) _Pragma("unroll") for (int k = 0; k < 2; ++k) dst[n][k] = *(const PG8_LAS bf16x8*)(lds + PG8_SB(b, h) + boff + n * 2048 + k * 1024); } while (0)
; #define PG8_MMA(ai, bj, At, Bt) do { __builtin_amdgcn_s_setprio(1); _Pragma("unroll") for (int m = 0; m < 4; ++m) _Pragma("unroll") for (int n = 0; n < 2; ++n) _Pragma("unroll") for (int k = 0; k < 2; ++k) \
;         acc[ai][bj][m][n] = __builtin_amdgcn_mfma_f32_16x16x32_bf16(Bt[n][k], At[m][k], acc[ai][bj][m][n], 0, 0, 0); __builtin_amdgcn_s_setprio(0); } while (0)
; #define PG8_WAIT_V(n) asm volatile("s_waitcnt vmcnt(" #n ")" ::: "memory")
; #define PG8_WAIT_L(n) asm volatile("s_waitcnt lgkmcnt(" #n ")" ::: "memory")
; #define PG8_BAR __builtin_amdgcn_s_barrier()
; #define PG8_SCHED __builtin_amdgcn_sched_barrier(0)
; template <class Epi, class Sched, bool ALIGN_EPI = false, bool SP2 = false>
; __device__ __forceinline__ void gemm_phase(PG8_LAS unsigned char* lds, const Gemm g, const Sched& S, const Epi& E, int tid_in) {
;     ...
;             PG8_LDB(B0, 1, 0); PG8_LDB(B1, 1, 1); PG8_SCHED; PG8_LDA(At, 1, 0); PG8_STAGE(PG8_SA(0, 1), a2 + hstep, voffA);
;             PG8_WAIT_V(8); PG8_WAIT_L(0); PG8_BAR; PG8_MMA(0, 0, At, B0); PG8_MMA(0, 1, At, B1); PG8_BAR; PG8_SCHED;
;             PG8_LDA(At, 1, 1); PG8_STAGE(PG8_SB(1, 0), b3, voffB); PG8_STAGE(PG8_SB(1, 1), b3 + hstep, voffB); PG8_STAGE(PG8_SA(1, 0), a3, voffA);
;             PG8_WAIT_V(8); PG8_WAIT_L(0); PG8_BAR; PG8_MMA(1, 0, At, B0); PG8_MMA(1, 1, At, B1); PG8_BAR; PG8_SCHED;
	s_setprio 1
	s_waitcnt lgkmcnt(0)
	v_mfma_f32_16x16x32_bf16 v[126:129], v[150:153], v[188:191], v[126:129]
	v_mfma_f32_16x16x32_bf16 v[122:125], v[158:161], v[188:191], v[122:125]
	v_mfma_f32_16x16x32_bf16 v[110:113], v[150:153], v[196:199], v[110:113]
	v_mfma_f32_16x16x32_bf16 v[106:109], v[158:161], v[196:199], v[106:109]
	v_mfma_f32_16x16x32_bf16 v[94:97], v[150:153], v[204:207], v[94:97]
	v_mfma_f32_16x16x32_bf16 v[90:93], v[158:161], v[204:207], v[90:93]
	v_mfma_f32_16x16x32_bf16 v[78:81], v[150:153], v[212:215], v[78:81]
	v_mfma_f32_16x16x32_bf16 v[74:77], v[158:161], v[212:215], v[74:77]
	v_mfma_f32_16x16x32_bf16 v[126:129], v[154:157], v[192:195], v[126:129]
	v_mfma_f32_16x16x32_bf16 v[122:125], v[162:165], v[192:195], v[122:125]
	v_mfma_f32_16x16x32_bf16 v[110:113], v[154:157], v[200:203], v[110:113]
	v_mfma_f32_16x16x32_bf16 v[106:109], v[162:165], v[200:203], v[106:109]
	v_mfma_f32_16x16x32_bf16 v[94:97], v[154:157], v[208:211], v[94:97]
	v_mfma_f32_16x16x32_bf16 v[90:93], v[162:165], v[208:211], v[90:93]
	v_mfma_f32_16x16x32_bf16 v[78:81], v[154:157], v[216:219], v[78:81]
	v_mfma_f32_16x16x32_bf16 v[74:77], v[162:165], v[216:219], v[74:77]
	v_mfma_f32_16x16x32_bf16 v[118:121], v[166:169], v[188:191], v[118:121]
	v_mfma_f32_16x16x32_bf16 v[114:117], v[180:183], v[188:191], v[114:117]
	v_mfma_f32_16x16x32_bf16 v[102:105], v[166:169], v[196:199], v[102:105]
	v_mfma_f32_16x16x32_bf16 v[98:101], v[180:183], v[196:199], v[98:101]
	v_mfma_f32_16x16x32_bf16 v[86:89], v[166:169], v[204:207], v[86:89]
	v_mfma_f32_16x16x32_bf16 v[82:85], v[180:183], v[204:207], v[82:85]
	v_mfma_f32_16x16x32_bf16 v[70:73], v[166:169], v[212:215], v[70:73]
	v_mfma_f32_16x16x32_bf16 v[66:69], v[180:183], v[212:215], v[66:69]
	v_mfma_f32_16x16x32_bf16 v[118:121], v[176:179], v[192:195], v[118:121]
	v_mfma_f32_16x16x32_bf16 v[114:117], v[184:187], v[192:195], v[114:117]
	v_mfma_f32_16x16x32_bf16 v[102:105], v[176:179], v[200:203], v[102:105]
	v_mfma_f32_16x16x32_bf16 v[98:101], v[184:187], v[200:203], v[98:101]
	v_mfma_f32_16x16x32_bf16 v[86:89], v[176:179], v[208:211], v[86:89]
	v_mfma_f32_16x16x32_bf16 v[82:85], v[184:187], v[208:211], v[82:85]
	v_mfma_f32_16x16x32_bf16 v[70:73], v[176:179], v[216:219], v[70:73]
	v_mfma_f32_16x16x32_bf16 v[66:69], v[184:187], v[216:219], v[66:69]
	s_setprio 0
	s_barrier
	s_add_i32 s30, s49, s6
	s_mov_b32 m0, s30
	ds_read_b128 v[188:191], v149 offset:49152
	ds_read_b128 v[192:195], v149 offset:50176
	ds_read_b128 v[196:199], v149 offset:51200
	ds_read_b128 v[200:203], v149 offset:52224
	ds_read_b128 v[204:207], v149 offset:53248
	ds_read_b128 v[208:211], v149 offset:54272
	ds_read_b128 v[212:215], v149 offset:55296
	ds_read_b128 v[216:219], v149 offset:56320
	s_add_u32 s98, s28, 0x80
	s_addc_u32 s99, s29, 0
	global_load_lds_dwordx4 v132, s[98:99]
	s_add_i32 m0, s30, 0x2000
	s_add_u32 s28, s28, 0x40080
	v_lshl_add_u64 v[142:143], v[170:171], 0, s[92:93]
	s_addc_u32 s29, s29, 0
	s_add_i32 s30, s50, s6
	global_load_lds_dwordx4 v[142:143], off
	s_mov_b32 m0, s30
	s_nop 0
	global_load_lds_dwordx4 v132, s[28:29]
	s_add_i32 m0, s30, 0x2000
	s_nop 0
	global_load_lds_dwordx4 v136, s[28:29]
	v_lshl_add_u64 v[142:143], v[220:221], 0, s[92:93]
	s_mov_b32 m0, s41
	s_nop 0
	global_load_lds_dwordx4 v[142:143], off
	v_lshl_add_u64 v[142:143], v[222:223], 0, s[92:93]
	s_mov_b32 m0, s42
	s_nop 0
	global_load_lds_dwordx4 v[142:143], off
	s_waitcnt vmcnt(8)
	s_waitcnt lgkmcnt(0)
	s_barrier
	s_setprio 1
	s_waitcnt lgkmcnt(0)
	v_mfma_f32_16x16x32_bf16 v[60:63], v[150:153], v[188:191], v[60:63]
	v_mfma_f32_16x16x32_bf16 v[56:59], v[158:161], v[188:191], v[56:59]
	v_mfma_f32_16x16x32_bf16 v[44:47], v[150:153], v[196:199], v[44:47]
	v_mfma_f32_16x16x32_bf16 v[40:43], v[158:161], v[196:199], v[40:43]
	v_mfma_f32_16x16x32_bf16 v[28:31], v[150:153], v[204:207], v[28:31]
	v_mfma_f32_16x16x32_bf16 v[24:27], v[158:161], v[204:207], v[24:27]
	v_mfma_f32_16x16x32_bf16 v[12:15], v[150:153], v[212:215], v[12:15]
	v_mfma_f32_16x16x32_bf16 v[8:11], v[158:161], v[212:215], v[8:11]
	v_mfma_f32_16x16x32_bf16 v[60:63], v[154:157], v[192:195], v[60:63]
	v_mfma_f32_16x16x32_bf16 v[56:59], v[162:165], v[192:195], v[56:59]
	v_mfma_f32_16x16x32_bf16 v[44:47], v[154:157], v[200:203], v[44:47]
	v_mfma_f32_16x16x32_bf16 v[40:43], v[162:165], v[200:203], v[40:43]
	v_mfma_f32_16x16x32_bf16 v[28:31], v[154:157], v[208:211], v[28:31]
	v_mfma_f32_16x16x32_bf16 v[24:27], v[162:165], v[208:211], v[24:27]
	v_mfma_f32_16x16x32_bf16 v[12:15], v[154:157], v[216:219], v[12:15]
	v_mfma_f32_16x16x32_bf16 v[8:11], v[162:165], v[216:219], v[8:11]
	v_mfma_f32_16x16x32_bf16 v[52:55], v[166:169], v[188:191], v[52:55]
	v_mfma_f32_16x16x32_bf16 v[48:51], v[180:183], v[188:191], v[48:51]
	v_mfma_f32_16x16x32_bf16 v[36:39], v[166:169], v[196:199], v[36:39]
	v_mfma_f32_16x16x32_bf16 v[32:35], v[180:183], v[196:199], v[32:35]
	v_mfma_f32_16x16x32_bf16 v[20:23], v[166:169], v[204:207], v[20:23]
	v_mfma_f32_16x16x32_bf16 v[16:19], v[180:183], v[204:207], v[16:19]
	v_mfma_f32_16x16x32_bf16 v[4:7], v[166:169], v[212:215], v[4:7]
	v_mfma_f32_16x16x32_bf16 v[0:3], v[180:183], v[212:215], v[0:3]
	v_mfma_f32_16x16x32_bf16 v[52:55], v[176:179], v[192:195], v[52:55]
	v_mfma_f32_16x16x32_bf16 v[48:51], v[184:187], v[192:195], v[48:51]
	v_mfma_f32_16x16x32_bf16 v[36:39], v[176:179], v[200:203], v[36:39]
	v_mfma_f32_16x16x32_bf16 v[32:35], v[184:187], v[200:203], v[32:35]
	v_mfma_f32_16x16x32_bf16 v[20:23], v[176:179], v[208:211], v[20:23]
	v_mfma_f32_16x16x32_bf16 v[16:19], v[184:187], v[208:211], v[16:19]
	v_mfma_f32_16x16x32_bf16 v[4:7], v[176:179], v[216:219], v[4:7]
	v_mfma_f32_16x16x32_bf16 v[0:3], v[184:187], v[216:219], v[0:3]
	s_setprio 0
	s_barrier
	s_add_i32 s48, s48, 2
	s_add_u32 s26, s26, 0x100
	s_addc_u32 s27, s27, 0
	s_add_u32 s46, s46, 0x100
	s_addc_u32 s47, s47, 0
	s_cmp_gt_u32 s48, 13
	s_cbranch_scc0 .LBB0_754
	s_branch .Lpeel_exit_0
